# baseline (speedup 1.0000x reference)
; __device__ __forceinline__ unsigned cvt_pk_bf16(float lo, float hi) { unsigned r; asm volatile("v_cvt_pk_bf16_f32 %0, %1, %2" : "=v"(r) : "v"(lo), "v"(hi)); return r; }
; __device__ __forceinline__ float dot4(f32x4 a, f32x4 b) { return (a.x * b.x + a.y * b.y) + (a.z * b.z + a.w * b.w); }
; __device__ __forceinline__ void group_norm_rows(const float* Y, const float* RW, const LayerP& L, bf16* dst, int gw, int NGW, int lane) {
;     for (int m = gw; m < T; m += NGW) {
; #pragma unroll
;         for (int gi = 0; gi < 4; ++gi) {
;             const float* yr = Y + (size_t)m * D + gi * GW;
;             f32x4 a = ((const f32x4*)yr)[lane], b = ((const f32x4*)yr)[64 + lane];
;             if (gi == 2) {
;                 const int ca = 4 * lane, cb = 256 + 4 * lane;
;                 const float ma = row16_sum((a.x + a.y) + (a.z + a.w)) * (1.f / 64.f), mb = row16_sum((b.x + b.y) + (b.z + b.w)) * (1.f / 64.f);
;                 const f32x4 da = a - ma, db = b - mb;
;                 const float ra = rsqrtf(row16_sum(dot4(da, da)) * (1.f / 64.f) + 64e-5f), rb = rsqrtf(row16_sum(dot4(db, db)) * (1.f / 64.f) + 64e-5f);
;                 const f32x4 ga = *(const f32x4*)(L.rw_lng + ca), gb = *(const f32x4*)(L.rw_lng + cb), ba = *(const f32x4*)(L.rw_lnb + ca), bb = *(const f32x4*)(L.rw_lnb + cb);
;                 const f32x4 bna = *(const f32x4*)(RW + 7 * RWSZ + (size_t)m * GW + ca), bnb = *(const f32x4*)(RW + 7 * RWSZ + (size_t)m * GW + cb);
;                 const f32x4 gga = *(const f32x4*)(RW + 6 * RWSZ + (size_t)m * GW + ca), ggb = *(const f32x4*)(RW + 6 * RWSZ + (size_t)m * GW + cb);
;                 a = (da * ra * ga + ba + bna) * gga; b = (db * rb * gb + bb + bnb) * ggb;
;             }
;             const float ss = wave_sum(dot4(a, a) + dot4(b, b));
;             const float rstd = rsqrtf(ss * (1.f / GW) + 1e-6f);
;             const f32x4 na = ((const f32x4*)(L.out_norm + gi * GW))[lane], nb = ((const f32x4*)(L.out_norm + gi * GW))[64 + lane];
;             const f32x4 oa = a * rstd * na, ob = b * rstd * nb;
;             u32x2 w; w.x = pg8::cvt_pk_bf16(oa.x, oa.y); w.y = pg8::cvt_pk_bf16(oa.z, oa.w); ((u32x2*)(dst + (size_t)m * D + gi * GW))[lane] = w;
;             w.x = pg8::cvt_pk_bf16(ob.x, ob.y); w.y = pg8::cvt_pk_bf16(ob.z, ob.w); ((u32x2*)(dst + (size_t)m * D + gi * GW))[64 + lane] = w;
.LBB0_61:
	s_and_b64 vcc, exec, s[0:1]
	v_readlane_b32 s14, v254, 42
	v_readlane_b32 s15, v254, 43
	s_cbranch_vccz .LBB0_65
	v_readlane_b32 s0, v254, 40
	s_cmpk_gt_i32 s0, 0x1fff
	v_readlane_b32 s1, v254, 41
	s_cbranch_scc1 .LBB0_65
	s_waitcnt vmcnt(0)
	v_readlane_b32 s8, v254, 32
	v_readlane_b32 s9, v254, 33
	v_readlane_b32 s10, v254, 30
	s_mov_b32 s30, s0
	s_load_dwordx2 s[4:5], s[8:9], 0x140
	s_load_dwordx4 s[20:23], s[8:9], 0xf8
	s_ashr_i32 s11, s10, 31
	v_lshlrev_b32_e32 v0, 4, v188
	v_add_u32_e32 v1, 0x1000, v0
	v_lshlrev_b32_e32 v2, 3, v188
	s_lshl_b64 s[0:1], s[10:11], 13
	s_lshl_b64 s[6:7], s[10:11], 11
	s_waitcnt lgkmcnt(0)
	s_add_u32 s4, s4, s0
	s_addc_u32 s5, s5, s1
	s_add_u32 s20, s20, s6
	s_addc_u32 s21, s21, s7
	s_add_u32 s22, s22, s6
	s_addc_u32 s23, s23, s7
	global_load_dwordx4 v[80:83], v0, s[4:5] offset:0
	global_load_dwordx4 v[84:87], v0, s[4:5] offset:1024
	global_load_dwordx4 v[88:91], v0, s[4:5] offset:2048
	global_load_dwordx4 v[92:95], v0, s[4:5] offset:3072
	global_load_dwordx4 v[96:99], v1, s[4:5] offset:0
	global_load_dwordx4 v[100:103], v1, s[4:5] offset:1024
	global_load_dwordx4 v[104:107], v1, s[4:5] offset:2048
	global_load_dwordx4 v[108:111], v1, s[4:5] offset:3072
	global_load_dwordx4 v[112:115], v0, s[20:21]
	global_load_dwordx4 v[116:119], v0, s[20:21] offset:1024
	global_load_dwordx4 v[120:123], v0, s[22:23]
	global_load_dwordx4 v[124:127], v0, s[22:23] offset:1024
.Lgn_row:
	s_lshl_b32 s0, s30, 13
	s_add_u32 s20, s18, s0
	s_addc_u32 s21, s19, 0
	s_add_u32 s20, s20, 0x1e200000
	s_addc_u32 s21, s21, 0
	s_lshl_b32 s0, s30, 11
	s_add_u32 s22, s18, s0
	s_addc_u32 s23, s19, 0
	s_add_u32 s24, s22, 0x1d200000
	s_addc_u32 s25, s23, 0
	s_add_u32 s22, s22, 0x1c200000
	s_addc_u32 s23, s23, 0
	s_lshl_b32 s0, s30, 12
	s_add_u32 s26, s18, s0
	s_addc_u32 s27, s19, 0
	s_add_u32 s26, s26, 0x22200000
	s_addc_u32 s27, s27, 0
	global_load_dwordx4 v[16:19], v0, s[20:21]
	global_load_dwordx4 v[20:23], v0, s[20:21] offset:1024
	global_load_dwordx4 v[24:27], v0, s[20:21] offset:2048
	global_load_dwordx4 v[28:31], v0, s[20:21] offset:3072
	global_load_dwordx4 v[40:43], v1, s[20:21] offset:2048
	global_load_dwordx4 v[44:47], v1, s[20:21] offset:3072
	global_load_dwordx4 v[32:35], v1, s[20:21]
	global_load_dwordx4 v[36:39], v1, s[20:21] offset:1024
	global_load_dwordx4 v[48:51], v0, s[24:25]
	global_load_dwordx4 v[52:55], v0, s[24:25] offset:1024
	global_load_dwordx4 v[56:59], v0, s[22:23]
	global_load_dwordx4 v[60:63], v0, s[22:23] offset:1024
	s_waitcnt vmcnt(10)
	v_mul_f32_e32 v3, v16, v16
	v_fmac_f32_e32 v3, v17, v17
	v_mul_f32_e32 v4, v18, v18
	v_fmac_f32_e32 v4, v19, v19
	v_add_f32_e32 v3, v3, v4
	v_mul_f32_e32 v5, v20, v20
	v_fmac_f32_e32 v5, v21, v21
	v_mul_f32_e32 v6, v22, v22
	v_fmac_f32_e32 v6, v23, v23
	v_add_f32_e32 v5, v5, v6
	v_add_f32_e32 v3, v3, v5
	s_nop 1
	v_add_f32_dpp v3, v3, v3 quad_perm:[1,0,3,2] row_mask:0xf bank_mask:0xf bound_ctrl:1
	s_nop 1
	v_add_f32_dpp v3, v3, v3 quad_perm:[2,3,0,1] row_mask:0xf bank_mask:0xf bound_ctrl:1
	s_nop 1
	v_add_f32_dpp v3, v3, v3 row_half_mirror row_mask:0xf bank_mask:0xf bound_ctrl:1
	s_nop 1
	v_add_f32_dpp v3, v3, v3 row_mirror row_mask:0xf bank_mask:0xf bound_ctrl:1
	s_nop 1
	v_readlane_b32 s0, v3, 0
	v_readlane_b32 s1, v3, 16
	v_readlane_b32 s8, v3, 32
	v_readlane_b32 s9, v3, 48
	s_nop 1
	v_mov_b32_e32 v4, s0
	v_add_f32_e32 v4, s1, v4
	v_add_f32_e32 v4, s8, v4
	v_add_f32_e32 v4, s9, v4
	v_mov_b32_e32 v5, 0x3b000000
	v_fma_f32 v4, v4, v5, v173
	v_rsq_f32_e32 v4, v4
	s_nop 0
	v_mul_f32_e32 v8, v16, v4
	v_mul_f32_e32 v8, v8, v80
	v_mul_f32_e32 v9, v17, v4
	v_mul_f32_e32 v9, v9, v81
	v_mul_f32_e32 v10, v18, v4
	v_mul_f32_e32 v10, v10, v82
	v_mul_f32_e32 v11, v19, v4
	v_mul_f32_e32 v11, v11, v83
	v_cvt_pk_bf16_f32 v12, v8, v9
	v_cvt_pk_bf16_f32 v13, v10, v11
	global_store_dwordx2 v2, v[12:13], s[26:27] offset:0
	v_mul_f32_e32 v8, v20, v4
	v_mul_f32_e32 v8, v8, v84
	v_mul_f32_e32 v9, v21, v4
	v_mul_f32_e32 v9, v9, v85
	v_mul_f32_e32 v10, v22, v4
	v_mul_f32_e32 v10, v10, v86
	v_mul_f32_e32 v11, v23, v4
	v_mul_f32_e32 v11, v11, v87
	v_cvt_pk_bf16_f32 v12, v8, v9
	v_cvt_pk_bf16_f32 v13, v10, v11
	global_store_dwordx2 v2, v[12:13], s[26:27] offset:512
	s_waitcnt vmcnt(10)
	v_mul_f32_e32 v3, v24, v24
	v_fmac_f32_e32 v3, v25, v25
	v_mul_f32_e32 v4, v26, v26
	v_fmac_f32_e32 v4, v27, v27
	v_add_f32_e32 v3, v3, v4
	v_mul_f32_e32 v5, v28, v28
	v_fmac_f32_e32 v5, v29, v29
	v_mul_f32_e32 v6, v30, v30
	v_fmac_f32_e32 v6, v31, v31
	v_add_f32_e32 v5, v5, v6
	v_add_f32_e32 v3, v3, v5
	s_nop 1
	v_add_f32_dpp v3, v3, v3 quad_perm:[1,0,3,2] row_mask:0xf bank_mask:0xf bound_ctrl:1
	s_nop 1
	v_add_f32_dpp v3, v3, v3 quad_perm:[2,3,0,1] row_mask:0xf bank_mask:0xf bound_ctrl:1
	s_nop 1
	v_add_f32_dpp v3, v3, v3 row_half_mirror row_mask:0xf bank_mask:0xf bound_ctrl:1
	s_nop 1
	v_add_f32_dpp v3, v3, v3 row_mirror row_mask:0xf bank_mask:0xf bound_ctrl:1
	s_nop 1
	v_readlane_b32 s0, v3, 0
	v_readlane_b32 s1, v3, 16
	v_readlane_b32 s8, v3, 32
	v_readlane_b32 s9, v3, 48
	s_nop 1
	v_mov_b32_e32 v4, s0
	v_add_f32_e32 v4, s1, v4
	v_add_f32_e32 v4, s8, v4
	v_add_f32_e32 v4, s9, v4
	v_mov_b32_e32 v5, 0x3b000000
	v_fma_f32 v4, v4, v5, v173
	v_rsq_f32_e32 v4, v4
	s_nop 0
	v_mul_f32_e32 v8, v24, v4
	v_mul_f32_e32 v8, v8, v88
	v_mul_f32_e32 v9, v25, v4
	v_mul_f32_e32 v9, v9, v89
	v_mul_f32_e32 v10, v26, v4
	v_mul_f32_e32 v10, v10, v90
	v_mul_f32_e32 v11, v27, v4
	v_mul_f32_e32 v11, v11, v91
	v_cvt_pk_bf16_f32 v12, v8, v9
	v_cvt_pk_bf16_f32 v13, v10, v11
	global_store_dwordx2 v2, v[12:13], s[26:27] offset:1024
	v_mul_f32_e32 v8, v28, v4
	v_mul_f32_e32 v8, v8, v92
	v_mul_f32_e32 v9, v29, v4
	v_mul_f32_e32 v9, v9, v93
	v_mul_f32_e32 v10, v30, v4
	v_mul_f32_e32 v10, v10, v94
	v_mul_f32_e32 v11, v31, v4
	v_mul_f32_e32 v11, v11, v95
	v_cvt_pk_bf16_f32 v12, v8, v9
	v_cvt_pk_bf16_f32 v13, v10, v11
	global_store_dwordx2 v2, v[12:13], s[26:27] offset:1536
	s_waitcnt vmcnt(10)
; __device__ __forceinline__ unsigned cvt_pk_bf16(float lo, float hi) { unsigned r; asm volatile("v_cvt_pk_bf16_f32 %0, %1, %2" : "=v"(r) : "v"(lo), "v"(hi)); return r; }
; __device__ __forceinline__ float dot4(f32x4 a, f32x4 b) { return (a.x * b.x + a.y * b.y) + (a.z * b.z + a.w * b.w); }
; __device__ __forceinline__ void group_norm_rows(const float* Y, const float* RW, const LayerP& L, bf16* dst, int gw, int NGW, int lane) {
;     ...
;             if (gi == 2) {
;                 const int ca = 4 * lane, cb = 256 + 4 * lane;
;                 const float ma = row16_sum((a.x + a.y) + (a.z + a.w)) * (1.f / 64.f), mb = row16_sum((b.x + b.y) + (b.z + b.w)) * (1.f / 64.f);
;                 const f32x4 da = a - ma, db = b - mb;
;                 const float ra = rsqrtf(row16_sum(dot4(da, da)) * (1.f / 64.f) + 64e-5f), rb = rsqrtf(row16_sum(dot4(db, db)) * (1.f / 64.f) + 64e-5f);
;                 const f32x4 ga = *(const f32x4*)(L.rw_lng + ca), gb = *(const f32x4*)(L.rw_lng + cb), ba = *(const f32x4*)(L.rw_lnb + ca), bb = *(const f32x4*)(L.rw_lnb + cb);
;                 const f32x4 bna = *(const f32x4*)(RW + 7 * RWSZ + (size_t)m * GW + ca), bnb = *(const f32x4*)(RW + 7 * RWSZ + (size_t)m * GW + cb);
;                 const f32x4 gga = *(const f32x4*)(RW + 6 * RWSZ + (size_t)m * GW + ca), ggb = *(const f32x4*)(RW + 6 * RWSZ + (size_t)m * GW + cb);
;                 a = (da * ra * ga + ba + bna) * gga; b = (db * rb * gb + bb + bnb) * ggb;
;             }
;             const float ss = wave_sum(dot4(a, a) + dot4(b, b));
;             const float rstd = rsqrtf(ss * (1.f / GW) + 1e-6f);
;             const f32x4 na = ((const f32x4*)(L.out_norm + gi * GW))[lane], nb = ((const f32x4*)(L.out_norm + gi * GW))[64 + lane];
;             const f32x4 oa = a * rstd * na, ob = b * rstd * nb;
;             u32x2 w; w.x = pg8::cvt_pk_bf16(oa.x, oa.y); w.y = pg8::cvt_pk_bf16(oa.z, oa.w); ((u32x2*)(dst + (size_t)m * D + gi * GW))[lane] = w;
;             w.x = pg8::cvt_pk_bf16(ob.x, ob.y); w.y = pg8::cvt_pk_bf16(ob.z, ob.w); ((u32x2*)(dst + (size_t)m * D + gi * GW))[64 + lane] = w;
;         }
;     }
	v_mul_f32_e32 v3, v40, v40
	v_fmac_f32_e32 v3, v41, v41
	v_mul_f32_e32 v4, v42, v42
	v_fmac_f32_e32 v4, v43, v43
	v_add_f32_e32 v3, v3, v4
	v_mul_f32_e32 v5, v44, v44
	v_fmac_f32_e32 v5, v45, v45
	v_mul_f32_e32 v6, v46, v46
	v_fmac_f32_e32 v6, v47, v47
	v_add_f32_e32 v5, v5, v6
	v_add_f32_e32 v3, v3, v5
	s_nop 1
	v_add_f32_dpp v3, v3, v3 quad_perm:[1,0,3,2] row_mask:0xf bank_mask:0xf bound_ctrl:1
	s_nop 1
	v_add_f32_dpp v3, v3, v3 quad_perm:[2,3,0,1] row_mask:0xf bank_mask:0xf bound_ctrl:1
	s_nop 1
	v_add_f32_dpp v3, v3, v3 row_half_mirror row_mask:0xf bank_mask:0xf bound_ctrl:1
	s_nop 1
	v_add_f32_dpp v3, v3, v3 row_mirror row_mask:0xf bank_mask:0xf bound_ctrl:1
	s_nop 1
	v_readlane_b32 s0, v3, 0
	v_readlane_b32 s1, v3, 16
	v_readlane_b32 s8, v3, 32
	v_readlane_b32 s9, v3, 48
	s_nop 1
	v_mov_b32_e32 v4, s0
	v_add_f32_e32 v4, s1, v4
	v_add_f32_e32 v4, s8, v4
	v_add_f32_e32 v4, s9, v4
	v_mov_b32_e32 v5, 0x3b000000
	v_fma_f32 v4, v4, v5, v173
	v_rsq_f32_e32 v4, v4
	s_nop 0
	v_mul_f32_e32 v8, v40, v4
	v_mul_f32_e32 v8, v8, v104
	v_mul_f32_e32 v9, v41, v4
	v_mul_f32_e32 v9, v9, v105
	v_mul_f32_e32 v10, v42, v4
	v_mul_f32_e32 v10, v10, v106
	v_mul_f32_e32 v11, v43, v4
	v_mul_f32_e32 v11, v11, v107
	v_cvt_pk_bf16_f32 v12, v8, v9
	v_cvt_pk_bf16_f32 v13, v10, v11
	global_store_dwordx2 v2, v[12:13], s[26:27] offset:3072
	v_mul_f32_e32 v8, v44, v4
	v_mul_f32_e32 v8, v8, v108
	v_mul_f32_e32 v9, v45, v4
	v_mul_f32_e32 v9, v9, v109
	v_mul_f32_e32 v10, v46, v4
	v_mul_f32_e32 v10, v10, v110
	v_mul_f32_e32 v11, v47, v4
	v_mul_f32_e32 v11, v11, v111
	v_cvt_pk_bf16_f32 v12, v8, v9
	v_cvt_pk_bf16_f32 v13, v10, v11
	global_store_dwordx2 v2, v[12:13], s[26:27] offset:3584
	s_waitcnt vmcnt(6)
	v_add_f32_e32 v64, v32, v33
	v_add_f32_e32 v3, v34, v35
	v_add_f32_e32 v64, v64, v3
	v_add_f32_e32 v65, v36, v37
	v_add_f32_e32 v3, v38, v39
	v_add_f32_e32 v65, v65, v3
	s_nop 1
	v_add_f32_dpp v64, v64, v64 quad_perm:[1,0,3,2] row_mask:0xf bank_mask:0xf bound_ctrl:1
	v_add_f32_dpp v65, v65, v65 quad_perm:[1,0,3,2] row_mask:0xf bank_mask:0xf bound_ctrl:1
	s_nop 1
	v_add_f32_dpp v64, v64, v64 quad_perm:[2,3,0,1] row_mask:0xf bank_mask:0xf bound_ctrl:1
	v_add_f32_dpp v65, v65, v65 quad_perm:[2,3,0,1] row_mask:0xf bank_mask:0xf bound_ctrl:1
	s_nop 1
	v_add_f32_dpp v64, v64, v64 row_half_mirror row_mask:0xf bank_mask:0xf bound_ctrl:1
	v_add_f32_dpp v65, v65, v65 row_half_mirror row_mask:0xf bank_mask:0xf bound_ctrl:1
	s_nop 1
	v_add_f32_dpp v64, v64, v64 row_mirror row_mask:0xf bank_mask:0xf bound_ctrl:1
	v_add_f32_dpp v65, v65, v65 row_mirror row_mask:0xf bank_mask:0xf bound_ctrl:1
	v_mul_f32_e32 v64, 0x3c800000, v64
	v_mul_f32_e32 v65, 0x3c800000, v65
	v_sub_f32_e32 v32, v32, v64
	v_sub_f32_e32 v36, v36, v65
	v_sub_f32_e32 v33, v33, v64
	v_sub_f32_e32 v37, v37, v65
	v_sub_f32_e32 v34, v34, v64
	v_sub_f32_e32 v38, v38, v65
	v_sub_f32_e32 v35, v35, v64
	v_sub_f32_e32 v39, v39, v65
	v_mul_f32_e32 v66, v32, v32
	v_fmac_f32_e32 v66, v33, v33
	v_mul_f32_e32 v3, v34, v34
	v_fmac_f32_e32 v3, v35, v35
	v_add_f32_e32 v66, v66, v3
	v_mul_f32_e32 v67, v36, v36
	v_fmac_f32_e32 v67, v37, v37
	v_mul_f32_e32 v3, v38, v38
	v_fmac_f32_e32 v3, v39, v39
	v_add_f32_e32 v67, v67, v3
	s_nop 1
	v_add_f32_dpp v66, v66, v66 quad_perm:[1,0,3,2] row_mask:0xf bank_mask:0xf bound_ctrl:1
	v_add_f32_dpp v67, v67, v67 quad_perm:[1,0,3,2] row_mask:0xf bank_mask:0xf bound_ctrl:1
	s_nop 1
	v_add_f32_dpp v66, v66, v66 quad_perm:[2,3,0,1] row_mask:0xf bank_mask:0xf bound_ctrl:1
	v_add_f32_dpp v67, v67, v67 quad_perm:[2,3,0,1] row_mask:0xf bank_mask:0xf bound_ctrl:1
	s_nop 1
	v_add_f32_dpp v66, v66, v66 row_half_mirror row_mask:0xf bank_mask:0xf bound_ctrl:1
	v_add_f32_dpp v67, v67, v67 row_half_mirror row_mask:0xf bank_mask:0xf bound_ctrl:1
	s_nop 1
	v_add_f32_dpp v66, v66, v66 row_mirror row_mask:0xf bank_mask:0xf bound_ctrl:1
	v_add_f32_dpp v67, v67, v67 row_mirror row_mask:0xf bank_mask:0xf bound_ctrl:1
	v_mov_b32_e32 v3, 0x3c800000
	v_mov_b32_e32 v5, 0x3a27c5ac
	v_fma_f32 v66, v66, v3, v5
	v_fma_f32 v67, v67, v3, v5
	v_rsq_f32_e32 v66, v66
	v_rsq_f32_e32 v67, v67
	s_nop 0
	v_mul_f32_e32 v32, v32, v66
	v_fma_f32 v32, v32, v112, v120
	v_add_f32_e32 v32, v32, v48
	v_mul_f32_e32 v32, v32, v56
	v_mul_f32_e32 v36, v36, v67
	v_fma_f32 v36, v36, v116, v124
	v_add_f32_e32 v36, v36, v52
	v_mul_f32_e32 v36, v36, v60
	v_mul_f32_e32 v33, v33, v66
	v_fma_f32 v33, v33, v113, v121
	v_add_f32_e32 v33, v33, v49
	v_mul_f32_e32 v33, v33, v57
	v_mul_f32_e32 v37, v37, v67
	v_fma_f32 v37, v37, v117, v125
	v_add_f32_e32 v37, v37, v53
	v_mul_f32_e32 v37, v37, v61
	v_mul_f32_e32 v34, v34, v66
	v_fma_f32 v34, v34, v114, v122
	v_add_f32_e32 v34, v34, v50
	v_mul_f32_e32 v34, v34, v58
	v_mul_f32_e32 v38, v38, v67
	v_fma_f32 v38, v38, v118, v126
	v_add_f32_e32 v38, v38, v54
	v_mul_f32_e32 v38, v38, v62
	v_mul_f32_e32 v35, v35, v66
	v_fma_f32 v35, v35, v115, v123
	v_add_f32_e32 v35, v35, v51
	v_mul_f32_e32 v35, v35, v59
	v_mul_f32_e32 v39, v39, v67
	v_fma_f32 v39, v39, v119, v127
	v_add_f32_e32 v39, v39, v55
	v_mul_f32_e32 v39, v39, v63
	v_mul_f32_e32 v3, v32, v32
	v_fmac_f32_e32 v3, v33, v33
	v_mul_f32_e32 v4, v34, v34
	v_fmac_f32_e32 v4, v35, v35
	v_add_f32_e32 v3, v3, v4
	v_mul_f32_e32 v5, v36, v36
	v_fmac_f32_e32 v5, v37, v37
	v_mul_f32_e32 v6, v38, v38
	v_fmac_f32_e32 v6, v39, v39
	v_add_f32_e32 v5, v5, v6
	v_add_f32_e32 v3, v3, v5
	s_nop 1
	v_add_f32_dpp v3, v3, v3 quad_perm:[1,0,3,2] row_mask:0xf bank_mask:0xf bound_ctrl:1
	s_nop 1
	v_add_f32_dpp v3, v3, v3 quad_perm:[2,3,0,1] row_mask:0xf bank_mask:0xf bound_ctrl:1
	s_nop 1
	v_add_f32_dpp v3, v3, v3 row_half_mirror row_mask:0xf bank_mask:0xf bound_ctrl:1
	s_nop 1
	v_add_f32_dpp v3, v3, v3 row_mirror row_mask:0xf bank_mask:0xf bound_ctrl:1
	s_nop 1
	v_readlane_b32 s0, v3, 0
	v_readlane_b32 s1, v3, 16
	v_readlane_b32 s8, v3, 32
	v_readlane_b32 s9, v3, 48
	s_nop 1
	v_mov_b32_e32 v4, s0
	v_add_f32_e32 v4, s1, v4
	v_add_f32_e32 v4, s8, v4
	v_add_f32_e32 v4, s9, v4
	v_mov_b32_e32 v5, 0x3b000000
	v_fma_f32 v4, v4, v5, v173
	v_rsq_f32_e32 v4, v4
	s_nop 0
	v_mul_f32_e32 v8, v32, v4
	v_mul_f32_e32 v8, v8, v96
	v_mul_f32_e32 v9, v33, v4
	v_mul_f32_e32 v9, v9, v97
	v_mul_f32_e32 v10, v34, v4
	v_mul_f32_e32 v10, v10, v98
	v_mul_f32_e32 v11, v35, v4
	v_mul_f32_e32 v11, v11, v99
	v_cvt_pk_bf16_f32 v12, v8, v9
	v_cvt_pk_bf16_f32 v13, v10, v11
	global_store_dwordx2 v2, v[12:13], s[26:27] offset:2048
	v_mul_f32_e32 v8, v36, v4
	v_mul_f32_e32 v8, v8, v100
	v_mul_f32_e32 v9, v37, v4
	v_mul_f32_e32 v9, v9, v101
	v_mul_f32_e32 v10, v38, v4
	v_mul_f32_e32 v10, v10, v102
	v_mul_f32_e32 v11, v39, v4
	v_mul_f32_e32 v11, v11, v103
	v_cvt_pk_bf16_f32 v12, v8, v9
	v_cvt_pk_bf16_f32 v13, v10, v11
	global_store_dwordx2 v2, v[12:13], s[26:27] offset:2560
	s_add_i32 s30, s30, s14
	s_cmpk_gt_i32 s30, 0x1fff
	s_cbranch_scc0 .Lgn_row
